# pool_unit sample-row d-pass hand-written: 8-slot software-pipelined load ring (was one round trip per row), on top of sort+epi+omov+pk5+vpair
# speedup vs baseline: 1.0070x; 1.0070x over previous
.LBB0_1131:
	s_and_b64 vcc, exec, s[8:9]
	s_cbranch_vccz .LBB0_1168
	v_lshlrev_b32_e32 v102, 1, v106
	s_waitcnt vmcnt(15)
	v_lshl_add_u64 v[2:3], s[6:7], 0, v[102:103]
	v_lshlrev_b32_e32 v102, 1, v104
	s_waitcnt vmcnt(3)
	v_lshl_add_u64 v[26:27], v[2:3], 0, v[102:103]
	v_lshlrev_b32_e32 v6, 1, v108
	v_mov_b32_e32 v7, v103
	v_lshl_add_u64 v[6:7], s[6:7], 0, v[6:7]
	v_add_co_u32_e32 v14, vcc, s35, v26
	v_lshl_add_u64 v[10:11], v[6:7], 0, v[102:103]
	s_nop 0
	v_addc_co_u32_e32 v15, vcc, 0, v27, vcc
	global_load_dwordx4 v[2:5], v[26:27], off
	global_load_dwordx4 v[66:69], v[26:27], off offset:256
	global_load_dwordx4 v[6:9], v[10:11], off
	global_load_dwordx4 v[70:73], v[10:11], off offset:256
	s_nop 0
	global_load_dwordx4 v[10:13], v[14:15], off
	global_load_dwordx4 v[74:77], v[14:15], off offset:256
	v_lshlrev_b32_e32 v14, 1, v110
	v_mov_b32_e32 v15, v103
	v_lshl_add_u64 v[14:15], s[6:7], 0, v[14:15]
	v_add_co_u32_e32 v22, vcc, s36, v26
	v_lshl_add_u64 v[18:19], v[14:15], 0, v[102:103]
	s_nop 0
	v_addc_co_u32_e32 v23, vcc, 0, v27, vcc
	global_load_dwordx4 v[14:17], v[18:19], off
	global_load_dwordx4 v[78:81], v[18:19], off offset:256
	s_nop 0
	global_load_dwordx4 v[18:21], v[22:23], off
	global_load_dwordx4 v[82:85], v[22:23], off offset:256
	v_lshlrev_b32_e32 v22, 1, v112
	v_mov_b32_e32 v23, v103
	v_lshl_add_u64 v[22:23], s[6:7], 0, v[22:23]
	s_waitcnt vmcnt(11)
	v_add_co_u32_e32 v30, vcc, s37, v26
	v_lshl_add_u64 v[28:29], v[22:23], 0, v[102:103]
	s_nop 0
	v_addc_co_u32_e32 v31, vcc, 0, v27, vcc
	global_load_dwordx4 v[22:25], v[28:29], off
	global_load_dwordx4 v[86:89], v[28:29], off offset:256
	s_nop 0
	global_load_dwordx4 v[26:29], v[30:31], off
	global_load_dwordx4 v[90:93], v[30:31], off offset:256
	v_lshlrev_b32_e32 v30, 1, v114
	v_mov_b32_e32 v31, v103
	v_lshl_add_u64 v[30:31], s[6:7], 0, v[30:31]
	v_lshl_add_u64 v[34:35], v[30:31], 0, v[102:103]
	global_load_dwordx4 v[30:33], v[34:35], off
	global_load_dwordx4 v[94:97], v[34:35], off offset:256
	v_cvt_f32_ubyte0_e32 v34, s46
	v_div_scale_f32 v35, s[6:7], v34, v34, 1.0
	v_rcp_f32_e32 v36, v35
	s_lshl_b32 s16, s47, 8
	s_cmp_eq_u32 s47, 0
	s_cselect_b64 s[6:7], -1, 0
	v_fma_f32 v37, -v35, v36, 1.0
	v_fmac_f32_e32 v36, v37, v36
	v_div_scale_f32 v37, vcc, 1.0, v34, 1.0
	v_mul_f32_e32 v38, v37, v36
	v_fma_f32 v39, -v35, v38, v37
	v_fmac_f32_e32 v38, v39, v36
	v_fma_f32 v35, -v35, v38, v37
	v_div_fmas_f32 v35, v35, v36, v38
	v_div_fixup_f32 v98, v35, v34, 1.0
	v_or_b32_e32 v34, s16, v182
	s_cmp_lg_u32 s47, 0
	v_lshlrev_b32_e32 v102, 1, v34
	s_cselect_b64 s[8:9], -1, 0
	v_lshl_add_u64 v[136:137], s[20:21], 0, v[102:103]
	v_lshlrev_b32_e32 v102, 2, v34
	s_and_b32 s10, s46, 2
	v_mov_b32_e32 v99, v98
	v_add_u32_e32 v100, s28, v1
	v_lshl_add_u64 v[138:139], v[132:133], 0, v[102:103]
	v_add_u32_e32 v135, s28, v183
	s_sub_i32 s47, 0, s10
	s_mov_b64 s[10:11], 0
	v_mov_b32_e32 v213, v0
	v_lshrrev_b32_e32 v138, 6, v0
	v_and_b32_e32 v100, 31, v0
	v_bfe_u32 v101, v0, 5, 1
	v_readfirstlane_b32 s48, v138
	v_lshlrev_b32_e32 v100, 3, v100
	v_lshl_add_u32 v101, v101, 3, v138
	v_or_b32_e32 v139, s16, v100
	v_mul_lo_u32 v160, v101, s30
	v_add_u32_e32 v246, s28, v101
	v_lshl_add_u32 v160, v100, 1, v160
	v_lshlrev_b32_e32 v161, 11, v246
	v_add_u32_e32 v247, 0xffffc000, v246
	v_lshl_add_u32 v161, v139, 1, v161
	v_lshrrev_b32_e32 v247, 3, v247
	v_mul_u32_u24_e32 v247, 15, v247
	v_add3_u32 v247, v247, v138, 15
	v_lshlrev_b32_e32 v135, 12, v247
	v_lshl_add_u32 v135, v139, 2, v135
	s_cmp_eq_u32 s46, 16
	s_cbranch_scc1 .Lpl_w16
	s_cmp_eq_u32 s46, 8
	s_cbranch_scc1 .Lpl_w8
	s_cmp_eq_u32 s46, 4
	s_cbranch_scc1 .Lpl_w4
	s_branch .Lpl_w2
.Lpl_w16:
	s_cmp_le_u32 0, s48
	s_cselect_b64 s[6:7], s[20:21], s[82:83]
	s_cselect_b64 vcc, -1, 0
	v_cndmask_b32_e32 v136, v135, v161, vcc
	global_load_dwordx4 v[34:37], v136, s[6:7]
	global_load_dwordx4 v[38:41], v136, s[6:7] offset:16
	s_cmp_le_u32 1, s48
	s_cselect_b64 s[6:7], s[20:21], s[82:83]
	s_cselect_b64 vcc, -1, 0
	v_subrev_u32_e32 v136, 0x800, v161
	v_subrev_u32_e32 v137, 0x1000, v135
	v_cndmask_b32_e32 v136, v137, v136, vcc
	global_load_dwordx4 v[42:45], v136, s[6:7]
	global_load_dwordx4 v[46:49], v136, s[6:7] offset:16
	s_cmp_le_u32 2, s48
	s_cselect_b64 s[6:7], s[20:21], s[82:83]
	s_cselect_b64 vcc, -1, 0
	v_subrev_u32_e32 v136, 0x1000, v161
	v_subrev_u32_e32 v137, 0x2000, v135
	v_cndmask_b32_e32 v136, v137, v136, vcc
	global_load_dwordx4 v[50:53], v136, s[6:7]
	global_load_dwordx4 v[54:57], v136, s[6:7] offset:16
	s_cmp_le_u32 3, s48
	s_cselect_b64 s[6:7], s[20:21], s[82:83]
	s_cselect_b64 vcc, -1, 0
	v_subrev_u32_e32 v136, 0x1800, v161
	v_subrev_u32_e32 v137, 0x3000, v135
	v_cndmask_b32_e32 v136, v137, v136, vcc
	global_load_dwordx4 v[58:61], v136, s[6:7]
	global_load_dwordx4 v[62:65], v136, s[6:7] offset:16
	s_cmp_le_u32 4, s48
	s_cselect_b64 s[6:7], s[20:21], s[82:83]
	s_cselect_b64 vcc, -1, 0
	v_subrev_u32_e32 v136, 0x2000, v161
	v_subrev_u32_e32 v137, 0x4000, v135
	v_cndmask_b32_e32 v136, v137, v136, vcc
	global_load_dwordx4 v[214:217], v136, s[6:7]
	global_load_dwordx4 v[218:221], v136, s[6:7] offset:16
	s_cmp_le_u32 5, s48
	s_cselect_b64 s[6:7], s[20:21], s[82:83]
	s_cselect_b64 vcc, -1, 0
	v_subrev_u32_e32 v136, 0x2800, v161
	v_subrev_u32_e32 v137, 0x5000, v135
	v_cndmask_b32_e32 v136, v137, v136, vcc
	global_load_dwordx4 v[222:225], v136, s[6:7]
	global_load_dwordx4 v[226:229], v136, s[6:7] offset:16
	s_cmp_le_u32 6, s48
	s_cselect_b64 s[6:7], s[20:21], s[82:83]
	s_cselect_b64 vcc, -1, 0
	v_subrev_u32_e32 v136, 0x3000, v161
	v_subrev_u32_e32 v137, 0x6000, v135
	v_cndmask_b32_e32 v136, v137, v136, vcc
	global_load_dwordx4 v[230:233], v136, s[6:7]
	global_load_dwordx4 v[234:237], v136, s[6:7] offset:16
	s_cmp_le_u32 7, s48
	s_cselect_b64 s[6:7], s[20:21], s[82:83]
	s_cselect_b64 vcc, -1, 0
	v_subrev_u32_e32 v136, 0x3800, v161
	v_subrev_u32_e32 v137, 0x7000, v135
	v_cndmask_b32_e32 v136, v137, v136, vcc
	global_load_dwordx4 v[238:241], v136, s[6:7]
	global_load_dwordx4 v[242:245], v136, s[6:7] offset:16
	s_mov_b32 s47, 7
.Lpl_w16_loop:
	s_waitcnt vmcnt(14)
	s_cmp_le_u32 0, s48
	s_cbranch_scc0 .Lpl_f1
	v_and_b32_e32 v41, 0xffff0000, v37
	v_lshlrev_b32_e32 v40, 16, v37
	v_and_b32_e32 v39, 0xffff0000, v36
	v_lshlrev_b32_e32 v38, 16, v36
	v_and_b32_e32 v37, 0xffff0000, v35
	v_lshlrev_b32_e32 v36, 16, v35
	v_and_b32_e32 v35, 0xffff0000, v34
	v_lshlrev_b32_e32 v34, 16, v34
.Lpl_f1:
	v_mov_b64_e32 v[148:149], v[34:35]
	v_mov_b64_e32 v[150:151], v[36:37]
	v_mov_b64_e32 v[152:153], v[38:39]
	v_mov_b64_e32 v[154:155], v[40:41]
	v_pk_add_f32 v[140:141], v[34:35], 0
	v_pk_add_f32 v[142:143], v[36:37], 0
	v_pk_add_f32 v[144:145], v[38:39], 0
	v_pk_add_f32 v[146:147], v[40:41], 0
	s_cmp_le_u32 8, s48
	s_cselect_b64 s[6:7], s[20:21], s[82:83]
	s_cselect_b64 vcc, -1, 0
	v_subrev_u32_e32 v136, 0x4000, v161
	v_subrev_u32_e32 v137, 0x8000, v135
	v_cndmask_b32_e32 v136, v137, v136, vcc
	global_load_dwordx4 v[34:37], v136, s[6:7]
	global_load_dwordx4 v[38:41], v136, s[6:7] offset:16
	s_waitcnt vmcnt(14)
	s_cmp_le_u32 1, s48
	s_cbranch_scc0 .Lpl_f2
	v_and_b32_e32 v49, 0xffff0000, v45
	v_lshlrev_b32_e32 v48, 16, v45
	v_and_b32_e32 v47, 0xffff0000, v44
	v_lshlrev_b32_e32 v46, 16, v44
	v_and_b32_e32 v45, 0xffff0000, v43
	v_lshlrev_b32_e32 v44, 16, v43
	v_and_b32_e32 v43, 0xffff0000, v42
	v_lshlrev_b32_e32 v42, 16, v42
.Lpl_f2:
	v_pk_add_f32 v[140:141], v[140:141], v[42:43]
	v_pk_add_f32 v[142:143], v[142:143], v[44:45]
	v_pk_add_f32 v[144:145], v[144:145], v[46:47]
	v_pk_add_f32 v[146:147], v[146:147], v[48:49]
	s_cmp_le_u32 9, s48
	s_cselect_b64 s[6:7], s[20:21], s[82:83]
	s_cselect_b64 vcc, -1, 0
	v_subrev_u32_e32 v136, 0x4800, v161
	v_subrev_u32_e32 v137, 0x9000, v135
	v_cndmask_b32_e32 v136, v137, v136, vcc
	global_load_dwordx4 v[42:45], v136, s[6:7]
	global_load_dwordx4 v[46:49], v136, s[6:7] offset:16
	s_waitcnt vmcnt(14)
	s_cmp_le_u32 2, s48
	s_cbranch_scc0 .Lpl_f3
	v_and_b32_e32 v57, 0xffff0000, v53
	v_lshlrev_b32_e32 v56, 16, v53
	v_and_b32_e32 v55, 0xffff0000, v52
	v_lshlrev_b32_e32 v54, 16, v52
	v_and_b32_e32 v53, 0xffff0000, v51
	v_lshlrev_b32_e32 v52, 16, v51
	v_and_b32_e32 v51, 0xffff0000, v50
	v_lshlrev_b32_e32 v50, 16, v50
.Lpl_f3:
	v_pk_add_f32 v[140:141], v[140:141], v[50:51]
	v_pk_add_f32 v[142:143], v[142:143], v[52:53]
	v_pk_add_f32 v[144:145], v[144:145], v[54:55]
	v_pk_add_f32 v[146:147], v[146:147], v[56:57]
	s_cmp_le_u32 10, s48
	s_cselect_b64 s[6:7], s[20:21], s[82:83]
	s_cselect_b64 vcc, -1, 0
	v_subrev_u32_e32 v136, 0x5000, v161
	v_subrev_u32_e32 v137, 0xa000, v135
	v_cndmask_b32_e32 v136, v137, v136, vcc
	global_load_dwordx4 v[50:53], v136, s[6:7]
	global_load_dwordx4 v[54:57], v136, s[6:7] offset:16
	s_waitcnt vmcnt(14)
	s_cmp_le_u32 3, s48
	s_cbranch_scc0 .Lpl_f4
	v_and_b32_e32 v65, 0xffff0000, v61
	v_lshlrev_b32_e32 v64, 16, v61
	v_and_b32_e32 v63, 0xffff0000, v60
	v_lshlrev_b32_e32 v62, 16, v60
	v_and_b32_e32 v61, 0xffff0000, v59
	v_lshlrev_b32_e32 v60, 16, v59
	v_and_b32_e32 v59, 0xffff0000, v58
	v_lshlrev_b32_e32 v58, 16, v58
.Lpl_f4:
	v_pk_add_f32 v[140:141], v[140:141], v[58:59]
	v_pk_add_f32 v[142:143], v[142:143], v[60:61]
	v_pk_add_f32 v[144:145], v[144:145], v[62:63]
	v_pk_add_f32 v[146:147], v[146:147], v[64:65]
	s_cmp_le_u32 11, s48
	s_cselect_b64 s[6:7], s[20:21], s[82:83]
	s_cselect_b64 vcc, -1, 0
	v_subrev_u32_e32 v136, 0x5800, v161
	v_subrev_u32_e32 v137, 0xb000, v135
	v_cndmask_b32_e32 v136, v137, v136, vcc
	global_load_dwordx4 v[58:61], v136, s[6:7]
	global_load_dwordx4 v[62:65], v136, s[6:7] offset:16
	s_waitcnt vmcnt(14)
	s_cmp_le_u32 4, s48
	s_cbranch_scc0 .Lpl_f5
	v_and_b32_e32 v221, 0xffff0000, v217
	v_lshlrev_b32_e32 v220, 16, v217
	v_and_b32_e32 v219, 0xffff0000, v216
	v_lshlrev_b32_e32 v218, 16, v216
	v_and_b32_e32 v217, 0xffff0000, v215
	v_lshlrev_b32_e32 v216, 16, v215
	v_and_b32_e32 v215, 0xffff0000, v214
	v_lshlrev_b32_e32 v214, 16, v214
.Lpl_f5:
	v_pk_add_f32 v[140:141], v[140:141], v[214:215]
	v_pk_add_f32 v[142:143], v[142:143], v[216:217]
	v_pk_add_f32 v[144:145], v[144:145], v[218:219]
	v_pk_add_f32 v[146:147], v[146:147], v[220:221]
	s_cmp_le_u32 12, s48
	s_cselect_b64 s[6:7], s[20:21], s[82:83]
	s_cselect_b64 vcc, -1, 0
	v_subrev_u32_e32 v136, 0x6000, v161
	v_subrev_u32_e32 v137, 0xc000, v135
	v_cndmask_b32_e32 v136, v137, v136, vcc
	global_load_dwordx4 v[214:217], v136, s[6:7]
	global_load_dwordx4 v[218:221], v136, s[6:7] offset:16
	s_waitcnt vmcnt(14)
	s_cmp_le_u32 5, s48
	s_cbranch_scc0 .Lpl_f6
	v_and_b32_e32 v229, 0xffff0000, v225
	v_lshlrev_b32_e32 v228, 16, v225
	v_and_b32_e32 v227, 0xffff0000, v224
	v_lshlrev_b32_e32 v226, 16, v224
	v_and_b32_e32 v225, 0xffff0000, v223
	v_lshlrev_b32_e32 v224, 16, v223
	v_and_b32_e32 v223, 0xffff0000, v222
	v_lshlrev_b32_e32 v222, 16, v222
.Lpl_f6:
	v_pk_add_f32 v[140:141], v[140:141], v[222:223]
	v_pk_add_f32 v[142:143], v[142:143], v[224:225]
	v_pk_add_f32 v[144:145], v[144:145], v[226:227]
	v_pk_add_f32 v[146:147], v[146:147], v[228:229]
	s_cmp_le_u32 13, s48
	s_cselect_b64 s[6:7], s[20:21], s[82:83]
	s_cselect_b64 vcc, -1, 0
	v_subrev_u32_e32 v136, 0x6800, v161
	v_subrev_u32_e32 v137, 0xd000, v135
	v_cndmask_b32_e32 v136, v137, v136, vcc
	global_load_dwordx4 v[222:225], v136, s[6:7]
	global_load_dwordx4 v[226:229], v136, s[6:7] offset:16
	s_waitcnt vmcnt(14)
	s_cmp_le_u32 6, s48
	s_cbranch_scc0 .Lpl_f7
	v_and_b32_e32 v237, 0xffff0000, v233
	v_lshlrev_b32_e32 v236, 16, v233
	v_and_b32_e32 v235, 0xffff0000, v232
	v_lshlrev_b32_e32 v234, 16, v232
	v_and_b32_e32 v233, 0xffff0000, v231
	v_lshlrev_b32_e32 v232, 16, v231
	v_and_b32_e32 v231, 0xffff0000, v230
	v_lshlrev_b32_e32 v230, 16, v230
.Lpl_f7:
	v_pk_add_f32 v[140:141], v[140:141], v[230:231]
	v_pk_add_f32 v[142:143], v[142:143], v[232:233]
	v_pk_add_f32 v[144:145], v[144:145], v[234:235]
	v_pk_add_f32 v[146:147], v[146:147], v[236:237]
	s_cmp_le_u32 14, s48
	s_cselect_b64 s[6:7], s[20:21], s[82:83]
	s_cselect_b64 vcc, -1, 0
	v_subrev_u32_e32 v136, 0x7000, v161
	v_subrev_u32_e32 v137, 0xe000, v135
	v_cndmask_b32_e32 v136, v137, v136, vcc
	global_load_dwordx4 v[230:233], v136, s[6:7]
	global_load_dwordx4 v[234:237], v136, s[6:7] offset:16
	s_waitcnt vmcnt(14)
	s_cmp_le_u32 7, s48
	s_cbranch_scc0 .Lpl_f8
	v_and_b32_e32 v245, 0xffff0000, v241
	v_lshlrev_b32_e32 v244, 16, v241
	v_and_b32_e32 v243, 0xffff0000, v240
	v_lshlrev_b32_e32 v242, 16, v240
	v_and_b32_e32 v241, 0xffff0000, v239
	v_lshlrev_b32_e32 v240, 16, v239
	v_and_b32_e32 v239, 0xffff0000, v238
	v_lshlrev_b32_e32 v238, 16, v238
.Lpl_f8:
	v_pk_add_f32 v[140:141], v[140:141], v[238:239]
	v_pk_add_f32 v[142:143], v[142:143], v[240:241]
	v_pk_add_f32 v[144:145], v[144:145], v[242:243]
	v_pk_add_f32 v[146:147], v[146:147], v[244:245]
	s_cmp_le_u32 15, s48
	s_cselect_b64 s[6:7], s[20:21], s[82:83]
	s_cselect_b64 vcc, -1, 0
	v_subrev_u32_e32 v136, 0x7800, v161
	v_subrev_u32_e32 v137, 0xf000, v135
	v_cndmask_b32_e32 v136, v137, v136, vcc
	global_load_dwordx4 v[238:241], v136, s[6:7]
	global_load_dwordx4 v[242:245], v136, s[6:7] offset:16
	s_waitcnt vmcnt(14)
	s_cmp_le_u32 8, s48
	s_cbranch_scc0 .Lpl_f9
	v_and_b32_e32 v41, 0xffff0000, v37
	v_lshlrev_b32_e32 v40, 16, v37
	v_and_b32_e32 v39, 0xffff0000, v36
	v_lshlrev_b32_e32 v38, 16, v36
	v_and_b32_e32 v37, 0xffff0000, v35
	v_lshlrev_b32_e32 v36, 16, v35
	v_and_b32_e32 v35, 0xffff0000, v34
	v_lshlrev_b32_e32 v34, 16, v34
.Lpl_f9:
	v_pk_add_f32 v[140:141], v[140:141], v[34:35]
	v_pk_add_f32 v[142:143], v[142:143], v[36:37]
	v_pk_add_f32 v[144:145], v[144:145], v[38:39]
	v_pk_add_f32 v[146:147], v[146:147], v[40:41]
	v_add_u32_e32 v161, 0x8000, v161
	v_add_u32_e32 v135, 0x1e000, v135
	s_cmp_le_u32 0, s48
	s_cselect_b64 s[6:7], s[20:21], s[82:83]
	s_cselect_b64 vcc, -1, 0
	v_cndmask_b32_e32 v136, v135, v161, vcc
	global_load_dwordx4 v[34:37], v136, s[6:7]
	global_load_dwordx4 v[38:41], v136, s[6:7] offset:16
	s_waitcnt vmcnt(14)
	s_cmp_le_u32 9, s48
	s_cbranch_scc0 .Lpl_f10
	v_and_b32_e32 v49, 0xffff0000, v45
	v_lshlrev_b32_e32 v48, 16, v45
	v_and_b32_e32 v47, 0xffff0000, v44
	v_lshlrev_b32_e32 v46, 16, v44
	v_and_b32_e32 v45, 0xffff0000, v43
	v_lshlrev_b32_e32 v44, 16, v43
	v_and_b32_e32 v43, 0xffff0000, v42
	v_lshlrev_b32_e32 v42, 16, v42
.Lpl_f10:
	v_pk_add_f32 v[140:141], v[140:141], v[42:43]
	v_pk_add_f32 v[142:143], v[142:143], v[44:45]
	v_pk_add_f32 v[144:145], v[144:145], v[46:47]
	v_pk_add_f32 v[146:147], v[146:147], v[48:49]
	s_cmp_le_u32 1, s48
	s_cselect_b64 s[6:7], s[20:21], s[82:83]
	s_cselect_b64 vcc, -1, 0
	v_subrev_u32_e32 v136, 0x800, v161
	v_subrev_u32_e32 v137, 0x1000, v135
	v_cndmask_b32_e32 v136, v137, v136, vcc
	global_load_dwordx4 v[42:45], v136, s[6:7]
	global_load_dwordx4 v[46:49], v136, s[6:7] offset:16
	s_waitcnt vmcnt(14)
	s_cmp_le_u32 10, s48
	s_cbranch_scc0 .Lpl_f11
	v_and_b32_e32 v57, 0xffff0000, v53
	v_lshlrev_b32_e32 v56, 16, v53
	v_and_b32_e32 v55, 0xffff0000, v52
	v_lshlrev_b32_e32 v54, 16, v52
	v_and_b32_e32 v53, 0xffff0000, v51
	v_lshlrev_b32_e32 v52, 16, v51
	v_and_b32_e32 v51, 0xffff0000, v50
	v_lshlrev_b32_e32 v50, 16, v50
.Lpl_f11:
	v_pk_add_f32 v[140:141], v[140:141], v[50:51]
	v_pk_add_f32 v[142:143], v[142:143], v[52:53]
	v_pk_add_f32 v[144:145], v[144:145], v[54:55]
	v_pk_add_f32 v[146:147], v[146:147], v[56:57]
	s_cmp_le_u32 2, s48
	s_cselect_b64 s[6:7], s[20:21], s[82:83]
	s_cselect_b64 vcc, -1, 0
	v_subrev_u32_e32 v136, 0x1000, v161
	v_subrev_u32_e32 v137, 0x2000, v135
	v_cndmask_b32_e32 v136, v137, v136, vcc
	global_load_dwordx4 v[50:53], v136, s[6:7]
	global_load_dwordx4 v[54:57], v136, s[6:7] offset:16
	s_waitcnt vmcnt(14)
	s_cmp_le_u32 11, s48
	s_cbranch_scc0 .Lpl_f12
	v_and_b32_e32 v65, 0xffff0000, v61
	v_lshlrev_b32_e32 v64, 16, v61
	v_and_b32_e32 v63, 0xffff0000, v60
	v_lshlrev_b32_e32 v62, 16, v60
	v_and_b32_e32 v61, 0xffff0000, v59
	v_lshlrev_b32_e32 v60, 16, v59
	v_and_b32_e32 v59, 0xffff0000, v58
	v_lshlrev_b32_e32 v58, 16, v58
.Lpl_f12:
	v_pk_add_f32 v[140:141], v[140:141], v[58:59]
	v_pk_add_f32 v[142:143], v[142:143], v[60:61]
	v_pk_add_f32 v[144:145], v[144:145], v[62:63]
	v_pk_add_f32 v[146:147], v[146:147], v[64:65]
	s_cmp_le_u32 3, s48
	s_cselect_b64 s[6:7], s[20:21], s[82:83]
	s_cselect_b64 vcc, -1, 0
	v_subrev_u32_e32 v136, 0x1800, v161
	v_subrev_u32_e32 v137, 0x3000, v135
	v_cndmask_b32_e32 v136, v137, v136, vcc
	global_load_dwordx4 v[58:61], v136, s[6:7]
	global_load_dwordx4 v[62:65], v136, s[6:7] offset:16
	s_waitcnt vmcnt(14)
	s_cmp_le_u32 12, s48
	s_cbranch_scc0 .Lpl_f13
	v_and_b32_e32 v221, 0xffff0000, v217
	v_lshlrev_b32_e32 v220, 16, v217
	v_and_b32_e32 v219, 0xffff0000, v216
	v_lshlrev_b32_e32 v218, 16, v216
	v_and_b32_e32 v217, 0xffff0000, v215
	v_lshlrev_b32_e32 v216, 16, v215
	v_and_b32_e32 v215, 0xffff0000, v214
	v_lshlrev_b32_e32 v214, 16, v214
.Lpl_f13:
	v_pk_add_f32 v[140:141], v[140:141], v[214:215]
	v_pk_add_f32 v[142:143], v[142:143], v[216:217]
	v_pk_add_f32 v[144:145], v[144:145], v[218:219]
	v_pk_add_f32 v[146:147], v[146:147], v[220:221]
	s_cmp_le_u32 4, s48
	s_cselect_b64 s[6:7], s[20:21], s[82:83]
	s_cselect_b64 vcc, -1, 0
	v_subrev_u32_e32 v136, 0x2000, v161
	v_subrev_u32_e32 v137, 0x4000, v135
	v_cndmask_b32_e32 v136, v137, v136, vcc
	global_load_dwordx4 v[214:217], v136, s[6:7]
	global_load_dwordx4 v[218:221], v136, s[6:7] offset:16
	s_waitcnt vmcnt(14)
	s_cmp_le_u32 13, s48
	s_cbranch_scc0 .Lpl_f14
	v_and_b32_e32 v229, 0xffff0000, v225
	v_lshlrev_b32_e32 v228, 16, v225
	v_and_b32_e32 v227, 0xffff0000, v224
	v_lshlrev_b32_e32 v226, 16, v224
	v_and_b32_e32 v225, 0xffff0000, v223
	v_lshlrev_b32_e32 v224, 16, v223
	v_and_b32_e32 v223, 0xffff0000, v222
	v_lshlrev_b32_e32 v222, 16, v222
.Lpl_f14:
	v_pk_add_f32 v[140:141], v[140:141], v[222:223]
	v_pk_add_f32 v[142:143], v[142:143], v[224:225]
	v_pk_add_f32 v[144:145], v[144:145], v[226:227]
	v_pk_add_f32 v[146:147], v[146:147], v[228:229]
	s_cmp_le_u32 5, s48
	s_cselect_b64 s[6:7], s[20:21], s[82:83]
	s_cselect_b64 vcc, -1, 0
	v_subrev_u32_e32 v136, 0x2800, v161
	v_subrev_u32_e32 v137, 0x5000, v135
	v_cndmask_b32_e32 v136, v137, v136, vcc
	global_load_dwordx4 v[222:225], v136, s[6:7]
	global_load_dwordx4 v[226:229], v136, s[6:7] offset:16
	s_waitcnt vmcnt(14)
	s_cmp_le_u32 14, s48
	s_cbranch_scc0 .Lpl_f15
	v_and_b32_e32 v237, 0xffff0000, v233
	v_lshlrev_b32_e32 v236, 16, v233
	v_and_b32_e32 v235, 0xffff0000, v232
	v_lshlrev_b32_e32 v234, 16, v232
	v_and_b32_e32 v233, 0xffff0000, v231
	v_lshlrev_b32_e32 v232, 16, v231
	v_and_b32_e32 v231, 0xffff0000, v230
	v_lshlrev_b32_e32 v230, 16, v230
.Lpl_f15:
	v_pk_add_f32 v[140:141], v[140:141], v[230:231]
	v_pk_add_f32 v[142:143], v[142:143], v[232:233]
	v_pk_add_f32 v[144:145], v[144:145], v[234:235]
	v_pk_add_f32 v[146:147], v[146:147], v[236:237]
	s_cmp_le_u32 6, s48
	s_cselect_b64 s[6:7], s[20:21], s[82:83]
	s_cselect_b64 vcc, -1, 0
	v_subrev_u32_e32 v136, 0x3000, v161
	v_subrev_u32_e32 v137, 0x6000, v135
	v_cndmask_b32_e32 v136, v137, v136, vcc
	global_load_dwordx4 v[230:233], v136, s[6:7]
	global_load_dwordx4 v[234:237], v136, s[6:7] offset:16
	s_waitcnt vmcnt(14)
	s_cmp_le_u32 15, s48
	s_cbranch_scc0 .Lpl_f16
	v_and_b32_e32 v245, 0xffff0000, v241
	v_lshlrev_b32_e32 v244, 16, v241
	v_and_b32_e32 v243, 0xffff0000, v240
	v_lshlrev_b32_e32 v242, 16, v240
	v_and_b32_e32 v241, 0xffff0000, v239
	v_lshlrev_b32_e32 v240, 16, v239
	v_and_b32_e32 v239, 0xffff0000, v238
	v_lshlrev_b32_e32 v238, 16, v238
.Lpl_f16:
	v_pk_add_f32 v[140:141], v[140:141], v[238:239]
	v_pk_add_f32 v[142:143], v[142:143], v[240:241]
	v_pk_add_f32 v[144:145], v[144:145], v[242:243]
	v_pk_add_f32 v[146:147], v[146:147], v[244:245]
	v_pk_fma_f32 v[140:141], v[98:99], v[140:141], v[148:149] neg_lo:[0,0,1] neg_hi:[0,0,1]
	v_pk_fma_f32 v[142:143], v[98:99], v[142:143], v[150:151] neg_lo:[0,0,1] neg_hi:[0,0,1]
	v_pk_fma_f32 v[144:145], v[98:99], v[144:145], v[152:153] neg_lo:[0,0,1] neg_hi:[0,0,1]
	v_pk_fma_f32 v[146:147], v[98:99], v[146:147], v[154:155] neg_lo:[0,0,1] neg_hi:[0,0,1]
	v_cvt_pk_bf16_f32 v156, v140, v141
	v_cvt_pk_bf16_f32 v157, v142, v143
	v_cvt_pk_bf16_f32 v158, v144, v145
	v_cvt_pk_bf16_f32 v159, v146, v147
	ds_write_b128 v160, v[156:159]
	v_add_u32_e32 v160, 0x2100, v160
	s_cmp_le_u32 7, s48
	s_cselect_b64 s[6:7], s[20:21], s[82:83]
	s_cselect_b64 vcc, -1, 0
	v_subrev_u32_e32 v136, 0x3800, v161
	v_subrev_u32_e32 v137, 0x7000, v135
	v_cndmask_b32_e32 v136, v137, v136, vcc
	global_load_dwordx4 v[238:241], v136, s[6:7]
	global_load_dwordx4 v[242:245], v136, s[6:7] offset:16
	s_add_i32 s47, s47, -1
	s_cmp_lg_u32 s47, 0
	s_cbranch_scc1 .Lpl_w16_loop
	s_waitcnt vmcnt(14)
	s_cmp_le_u32 0, s48
	s_cbranch_scc0 .Lpl_f17
	v_and_b32_e32 v41, 0xffff0000, v37
	v_lshlrev_b32_e32 v40, 16, v37
	v_and_b32_e32 v39, 0xffff0000, v36
	v_lshlrev_b32_e32 v38, 16, v36
	v_and_b32_e32 v37, 0xffff0000, v35
	v_lshlrev_b32_e32 v36, 16, v35
	v_and_b32_e32 v35, 0xffff0000, v34
	v_lshlrev_b32_e32 v34, 16, v34

.Lpl_f25:
	v_pk_add_f32 v[140:141], v[140:141], v[34:35]
	v_pk_add_f32 v[142:143], v[142:143], v[36:37]
	v_pk_add_f32 v[144:145], v[144:145], v[38:39]
	v_pk_add_f32 v[146:147], v[146:147], v[40:41]
	s_waitcnt vmcnt(12)
	s_cmp_le_u32 9, s48
	s_cbranch_scc0 .Lpl_f26
	v_and_b32_e32 v49, 0xffff0000, v45
	v_lshlrev_b32_e32 v48, 16, v45
	v_and_b32_e32 v47, 0xffff0000, v44
	v_lshlrev_b32_e32 v46, 16, v44
	v_and_b32_e32 v45, 0xffff0000, v43
	v_lshlrev_b32_e32 v44, 16, v43
	v_and_b32_e32 v43, 0xffff0000, v42
	v_lshlrev_b32_e32 v42, 16, v42
.Lpl_f26:
	v_pk_add_f32 v[140:141], v[140:141], v[42:43]
	v_pk_add_f32 v[142:143], v[142:143], v[44:45]
	v_pk_add_f32 v[144:145], v[144:145], v[46:47]
	v_pk_add_f32 v[146:147], v[146:147], v[48:49]
	s_waitcnt vmcnt(10)
	s_cmp_le_u32 10, s48
	s_cbranch_scc0 .Lpl_f27
	v_and_b32_e32 v57, 0xffff0000, v53
	v_lshlrev_b32_e32 v56, 16, v53
	v_and_b32_e32 v55, 0xffff0000, v52
	v_lshlrev_b32_e32 v54, 16, v52
	v_and_b32_e32 v53, 0xffff0000, v51
	v_lshlrev_b32_e32 v52, 16, v51
	v_and_b32_e32 v51, 0xffff0000, v50
	v_lshlrev_b32_e32 v50, 16, v50
.Lpl_f27:
	v_pk_add_f32 v[140:141], v[140:141], v[50:51]
	v_pk_add_f32 v[142:143], v[142:143], v[52:53]
	v_pk_add_f32 v[144:145], v[144:145], v[54:55]
	v_pk_add_f32 v[146:147], v[146:147], v[56:57]
	s_waitcnt vmcnt(8)
	s_cmp_le_u32 11, s48
	s_cbranch_scc0 .Lpl_f28
	v_and_b32_e32 v65, 0xffff0000, v61
	v_lshlrev_b32_e32 v64, 16, v61
	v_and_b32_e32 v63, 0xffff0000, v60
	v_lshlrev_b32_e32 v62, 16, v60
	v_and_b32_e32 v61, 0xffff0000, v59
	v_lshlrev_b32_e32 v60, 16, v59
	v_and_b32_e32 v59, 0xffff0000, v58
	v_lshlrev_b32_e32 v58, 16, v58
.Lpl_f28:
	v_pk_add_f32 v[140:141], v[140:141], v[58:59]
	v_pk_add_f32 v[142:143], v[142:143], v[60:61]
	v_pk_add_f32 v[144:145], v[144:145], v[62:63]
	v_pk_add_f32 v[146:147], v[146:147], v[64:65]
	s_waitcnt vmcnt(6)
	s_cmp_le_u32 12, s48
	s_cbranch_scc0 .Lpl_f29
	v_and_b32_e32 v221, 0xffff0000, v217
	v_lshlrev_b32_e32 v220, 16, v217
	v_and_b32_e32 v219, 0xffff0000, v216
	v_lshlrev_b32_e32 v218, 16, v216
	v_and_b32_e32 v217, 0xffff0000, v215
	v_lshlrev_b32_e32 v216, 16, v215
	v_and_b32_e32 v215, 0xffff0000, v214
	v_lshlrev_b32_e32 v214, 16, v214
.Lpl_f29:
	v_pk_add_f32 v[140:141], v[140:141], v[214:215]
	v_pk_add_f32 v[142:143], v[142:143], v[216:217]
	v_pk_add_f32 v[144:145], v[144:145], v[218:219]
	v_pk_add_f32 v[146:147], v[146:147], v[220:221]
	s_waitcnt vmcnt(4)
	s_cmp_le_u32 13, s48
	s_cbranch_scc0 .Lpl_f30
	v_and_b32_e32 v229, 0xffff0000, v225
	v_lshlrev_b32_e32 v228, 16, v225
	v_and_b32_e32 v227, 0xffff0000, v224
	v_lshlrev_b32_e32 v226, 16, v224
	v_and_b32_e32 v225, 0xffff0000, v223
	v_lshlrev_b32_e32 v224, 16, v223
	v_and_b32_e32 v223, 0xffff0000, v222
	v_lshlrev_b32_e32 v222, 16, v222
.Lpl_f30:
	v_pk_add_f32 v[140:141], v[140:141], v[222:223]
	v_pk_add_f32 v[142:143], v[142:143], v[224:225]
	v_pk_add_f32 v[144:145], v[144:145], v[226:227]
	v_pk_add_f32 v[146:147], v[146:147], v[228:229]
	s_waitcnt vmcnt(2)
	s_cmp_le_u32 14, s48
	s_cbranch_scc0 .Lpl_f31
	v_and_b32_e32 v237, 0xffff0000, v233
	v_lshlrev_b32_e32 v236, 16, v233
	v_and_b32_e32 v235, 0xffff0000, v232
	v_lshlrev_b32_e32 v234, 16, v232
	v_and_b32_e32 v233, 0xffff0000, v231
	v_lshlrev_b32_e32 v232, 16, v231
	v_and_b32_e32 v231, 0xffff0000, v230
	v_lshlrev_b32_e32 v230, 16, v230
.Lpl_f31:
	v_pk_add_f32 v[140:141], v[140:141], v[230:231]
	v_pk_add_f32 v[142:143], v[142:143], v[232:233]
	v_pk_add_f32 v[144:145], v[144:145], v[234:235]
	v_pk_add_f32 v[146:147], v[146:147], v[236:237]
	s_waitcnt vmcnt(0)
	s_cmp_le_u32 15, s48
	s_cbranch_scc0 .Lpl_f32
	v_and_b32_e32 v245, 0xffff0000, v241
	v_lshlrev_b32_e32 v244, 16, v241
	v_and_b32_e32 v243, 0xffff0000, v240
	v_lshlrev_b32_e32 v242, 16, v240
	v_and_b32_e32 v241, 0xffff0000, v239
	v_lshlrev_b32_e32 v240, 16, v239
	v_and_b32_e32 v239, 0xffff0000, v238
	v_lshlrev_b32_e32 v238, 16, v238
.Lpl_f32:
	v_pk_add_f32 v[140:141], v[140:141], v[238:239]
	v_pk_add_f32 v[142:143], v[142:143], v[240:241]
	v_pk_add_f32 v[144:145], v[144:145], v[242:243]
	v_pk_add_f32 v[146:147], v[146:147], v[244:245]
	v_pk_fma_f32 v[140:141], v[98:99], v[140:141], v[148:149] neg_lo:[0,0,1] neg_hi:[0,0,1]
	v_pk_fma_f32 v[142:143], v[98:99], v[142:143], v[150:151] neg_lo:[0,0,1] neg_hi:[0,0,1]
	v_pk_fma_f32 v[144:145], v[98:99], v[144:145], v[152:153] neg_lo:[0,0,1] neg_hi:[0,0,1]
	v_pk_fma_f32 v[146:147], v[98:99], v[146:147], v[154:155] neg_lo:[0,0,1] neg_hi:[0,0,1]
	v_cvt_pk_bf16_f32 v156, v140, v141
	v_cvt_pk_bf16_f32 v157, v142, v143
	v_cvt_pk_bf16_f32 v158, v144, v145
	v_cvt_pk_bf16_f32 v159, v146, v147
	ds_write_b128 v160, v[156:159]
	v_add_u32_e32 v160, 0x2100, v160
	s_branch .Lpl_done

.Lpl_f33:
	v_mov_b64_e32 v[148:149], v[34:35]
	v_mov_b64_e32 v[150:151], v[36:37]
	v_mov_b64_e32 v[152:153], v[38:39]
	v_mov_b64_e32 v[154:155], v[40:41]
	v_pk_add_f32 v[140:141], v[34:35], 0
	v_pk_add_f32 v[142:143], v[36:37], 0
	v_pk_add_f32 v[144:145], v[38:39], 0
	v_pk_add_f32 v[146:147], v[40:41], 0
	v_add_u32_e32 v161, 0x8000, v161
	v_add_u32_e32 v135, 0x1e000, v135
	s_cmp_le_u32 0, s48
	s_cselect_b64 s[6:7], s[20:21], s[82:83]
	s_cselect_b64 vcc, -1, 0
	v_cndmask_b32_e32 v136, v135, v161, vcc
	global_load_dwordx4 v[34:37], v136, s[6:7]
	global_load_dwordx4 v[38:41], v136, s[6:7] offset:16
	s_waitcnt vmcnt(14)
	s_cmp_le_u32 1, s48
	s_cbranch_scc0 .Lpl_f34
	v_and_b32_e32 v49, 0xffff0000, v45
	v_lshlrev_b32_e32 v48, 16, v45
	v_and_b32_e32 v47, 0xffff0000, v44
	v_lshlrev_b32_e32 v46, 16, v44
	v_and_b32_e32 v45, 0xffff0000, v43
	v_lshlrev_b32_e32 v44, 16, v43
	v_and_b32_e32 v43, 0xffff0000, v42
	v_lshlrev_b32_e32 v42, 16, v42
.Lpl_f34:
	v_pk_add_f32 v[140:141], v[140:141], v[42:43]
	v_pk_add_f32 v[142:143], v[142:143], v[44:45]
	v_pk_add_f32 v[144:145], v[144:145], v[46:47]
	v_pk_add_f32 v[146:147], v[146:147], v[48:49]
	s_cmp_le_u32 1, s48
	s_cselect_b64 s[6:7], s[20:21], s[82:83]
	s_cselect_b64 vcc, -1, 0
	v_subrev_u32_e32 v136, 0x800, v161
	v_subrev_u32_e32 v137, 0x1000, v135
	v_cndmask_b32_e32 v136, v137, v136, vcc
	global_load_dwordx4 v[42:45], v136, s[6:7]
	global_load_dwordx4 v[46:49], v136, s[6:7] offset:16
	s_waitcnt vmcnt(14)
	s_cmp_le_u32 2, s48
	s_cbranch_scc0 .Lpl_f35
	v_and_b32_e32 v57, 0xffff0000, v53
	v_lshlrev_b32_e32 v56, 16, v53
	v_and_b32_e32 v55, 0xffff0000, v52
	v_lshlrev_b32_e32 v54, 16, v52
	v_and_b32_e32 v53, 0xffff0000, v51
	v_lshlrev_b32_e32 v52, 16, v51
	v_and_b32_e32 v51, 0xffff0000, v50
	v_lshlrev_b32_e32 v50, 16, v50
.Lpl_f35:
	v_pk_add_f32 v[140:141], v[140:141], v[50:51]
	v_pk_add_f32 v[142:143], v[142:143], v[52:53]
	v_pk_add_f32 v[144:145], v[144:145], v[54:55]
	v_pk_add_f32 v[146:147], v[146:147], v[56:57]
	s_cmp_le_u32 2, s48
	s_cselect_b64 s[6:7], s[20:21], s[82:83]
	s_cselect_b64 vcc, -1, 0
	v_subrev_u32_e32 v136, 0x1000, v161
	v_subrev_u32_e32 v137, 0x2000, v135
	v_cndmask_b32_e32 v136, v137, v136, vcc
	global_load_dwordx4 v[50:53], v136, s[6:7]
	global_load_dwordx4 v[54:57], v136, s[6:7] offset:16
	s_waitcnt vmcnt(14)
	s_cmp_le_u32 3, s48
	s_cbranch_scc0 .Lpl_f36
	v_and_b32_e32 v65, 0xffff0000, v61
	v_lshlrev_b32_e32 v64, 16, v61
	v_and_b32_e32 v63, 0xffff0000, v60
	v_lshlrev_b32_e32 v62, 16, v60
	v_and_b32_e32 v61, 0xffff0000, v59
	v_lshlrev_b32_e32 v60, 16, v59
	v_and_b32_e32 v59, 0xffff0000, v58
	v_lshlrev_b32_e32 v58, 16, v58
.Lpl_f36:
	v_pk_add_f32 v[140:141], v[140:141], v[58:59]
	v_pk_add_f32 v[142:143], v[142:143], v[60:61]
	v_pk_add_f32 v[144:145], v[144:145], v[62:63]
	v_pk_add_f32 v[146:147], v[146:147], v[64:65]
	s_cmp_le_u32 3, s48
	s_cselect_b64 s[6:7], s[20:21], s[82:83]
	s_cselect_b64 vcc, -1, 0
	v_subrev_u32_e32 v136, 0x1800, v161
	v_subrev_u32_e32 v137, 0x3000, v135
	v_cndmask_b32_e32 v136, v137, v136, vcc
	global_load_dwordx4 v[58:61], v136, s[6:7]
	global_load_dwordx4 v[62:65], v136, s[6:7] offset:16
	s_waitcnt vmcnt(14)
	s_cmp_le_u32 4, s48
	s_cbranch_scc0 .Lpl_f37
	v_and_b32_e32 v221, 0xffff0000, v217
	v_lshlrev_b32_e32 v220, 16, v217
	v_and_b32_e32 v219, 0xffff0000, v216
	v_lshlrev_b32_e32 v218, 16, v216
	v_and_b32_e32 v217, 0xffff0000, v215
	v_lshlrev_b32_e32 v216, 16, v215
	v_and_b32_e32 v215, 0xffff0000, v214
	v_lshlrev_b32_e32 v214, 16, v214
.Lpl_f37:
	v_pk_add_f32 v[140:141], v[140:141], v[214:215]
	v_pk_add_f32 v[142:143], v[142:143], v[216:217]
	v_pk_add_f32 v[144:145], v[144:145], v[218:219]
	v_pk_add_f32 v[146:147], v[146:147], v[220:221]
	s_cmp_le_u32 4, s48
	s_cselect_b64 s[6:7], s[20:21], s[82:83]
	s_cselect_b64 vcc, -1, 0
	v_subrev_u32_e32 v136, 0x2000, v161
	v_subrev_u32_e32 v137, 0x4000, v135
	v_cndmask_b32_e32 v136, v137, v136, vcc
	global_load_dwordx4 v[214:217], v136, s[6:7]
	global_load_dwordx4 v[218:221], v136, s[6:7] offset:16
	s_waitcnt vmcnt(14)
	s_cmp_le_u32 5, s48
	s_cbranch_scc0 .Lpl_f38
	v_and_b32_e32 v229, 0xffff0000, v225
	v_lshlrev_b32_e32 v228, 16, v225
	v_and_b32_e32 v227, 0xffff0000, v224
	v_lshlrev_b32_e32 v226, 16, v224
	v_and_b32_e32 v225, 0xffff0000, v223
	v_lshlrev_b32_e32 v224, 16, v223
	v_and_b32_e32 v223, 0xffff0000, v222
	v_lshlrev_b32_e32 v222, 16, v222
.Lpl_f38:
	v_pk_add_f32 v[140:141], v[140:141], v[222:223]
	v_pk_add_f32 v[142:143], v[142:143], v[224:225]
	v_pk_add_f32 v[144:145], v[144:145], v[226:227]
	v_pk_add_f32 v[146:147], v[146:147], v[228:229]
	s_cmp_le_u32 5, s48
	s_cselect_b64 s[6:7], s[20:21], s[82:83]
	s_cselect_b64 vcc, -1, 0
	v_subrev_u32_e32 v136, 0x2800, v161
	v_subrev_u32_e32 v137, 0x5000, v135
	v_cndmask_b32_e32 v136, v137, v136, vcc
	global_load_dwordx4 v[222:225], v136, s[6:7]
	global_load_dwordx4 v[226:229], v136, s[6:7] offset:16
	s_waitcnt vmcnt(14)
	s_cmp_le_u32 6, s48
	s_cbranch_scc0 .Lpl_f39
	v_and_b32_e32 v237, 0xffff0000, v233
	v_lshlrev_b32_e32 v236, 16, v233
	v_and_b32_e32 v235, 0xffff0000, v232
	v_lshlrev_b32_e32 v234, 16, v232
	v_and_b32_e32 v233, 0xffff0000, v231
	v_lshlrev_b32_e32 v232, 16, v231
	v_and_b32_e32 v231, 0xffff0000, v230
	v_lshlrev_b32_e32 v230, 16, v230
.Lpl_f39:
	v_pk_add_f32 v[140:141], v[140:141], v[230:231]
	v_pk_add_f32 v[142:143], v[142:143], v[232:233]
	v_pk_add_f32 v[144:145], v[144:145], v[234:235]
	v_pk_add_f32 v[146:147], v[146:147], v[236:237]
	s_cmp_le_u32 6, s48
	s_cselect_b64 s[6:7], s[20:21], s[82:83]
	s_cselect_b64 vcc, -1, 0
	v_subrev_u32_e32 v136, 0x3000, v161
	v_subrev_u32_e32 v137, 0x6000, v135
	v_cndmask_b32_e32 v136, v137, v136, vcc
	global_load_dwordx4 v[230:233], v136, s[6:7]
	global_load_dwordx4 v[234:237], v136, s[6:7] offset:16
	s_waitcnt vmcnt(14)
	s_cmp_le_u32 7, s48
	s_cbranch_scc0 .Lpl_f40
	v_and_b32_e32 v245, 0xffff0000, v241
	v_lshlrev_b32_e32 v244, 16, v241
	v_and_b32_e32 v243, 0xffff0000, v240
	v_lshlrev_b32_e32 v242, 16, v240
	v_and_b32_e32 v241, 0xffff0000, v239
	v_lshlrev_b32_e32 v240, 16, v239
	v_and_b32_e32 v239, 0xffff0000, v238
	v_lshlrev_b32_e32 v238, 16, v238

.Lpl_f41:
	v_mov_b64_e32 v[148:149], v[34:35]
	v_mov_b64_e32 v[150:151], v[36:37]
	v_mov_b64_e32 v[152:153], v[38:39]
	v_mov_b64_e32 v[154:155], v[40:41]
	v_pk_add_f32 v[140:141], v[34:35], 0
	v_pk_add_f32 v[142:143], v[36:37], 0
	v_pk_add_f32 v[144:145], v[38:39], 0
	v_pk_add_f32 v[146:147], v[40:41], 0
	s_waitcnt vmcnt(12)
	s_cmp_le_u32 1, s48
	s_cbranch_scc0 .Lpl_f42
	v_and_b32_e32 v49, 0xffff0000, v45
	v_lshlrev_b32_e32 v48, 16, v45
	v_and_b32_e32 v47, 0xffff0000, v44
	v_lshlrev_b32_e32 v46, 16, v44
	v_and_b32_e32 v45, 0xffff0000, v43
	v_lshlrev_b32_e32 v44, 16, v43
	v_and_b32_e32 v43, 0xffff0000, v42
	v_lshlrev_b32_e32 v42, 16, v42
.Lpl_f42:
	v_pk_add_f32 v[140:141], v[140:141], v[42:43]
	v_pk_add_f32 v[142:143], v[142:143], v[44:45]
	v_pk_add_f32 v[144:145], v[144:145], v[46:47]
	v_pk_add_f32 v[146:147], v[146:147], v[48:49]
	s_waitcnt vmcnt(10)
	s_cmp_le_u32 2, s48
	s_cbranch_scc0 .Lpl_f43
	v_and_b32_e32 v57, 0xffff0000, v53
	v_lshlrev_b32_e32 v56, 16, v53
	v_and_b32_e32 v55, 0xffff0000, v52
	v_lshlrev_b32_e32 v54, 16, v52
	v_and_b32_e32 v53, 0xffff0000, v51
	v_lshlrev_b32_e32 v52, 16, v51
	v_and_b32_e32 v51, 0xffff0000, v50
	v_lshlrev_b32_e32 v50, 16, v50
.Lpl_f43:
	v_pk_add_f32 v[140:141], v[140:141], v[50:51]
	v_pk_add_f32 v[142:143], v[142:143], v[52:53]
	v_pk_add_f32 v[144:145], v[144:145], v[54:55]
	v_pk_add_f32 v[146:147], v[146:147], v[56:57]
	s_waitcnt vmcnt(8)
	s_cmp_le_u32 3, s48
	s_cbranch_scc0 .Lpl_f44
	v_and_b32_e32 v65, 0xffff0000, v61
	v_lshlrev_b32_e32 v64, 16, v61
	v_and_b32_e32 v63, 0xffff0000, v60
	v_lshlrev_b32_e32 v62, 16, v60
	v_and_b32_e32 v61, 0xffff0000, v59
	v_lshlrev_b32_e32 v60, 16, v59
	v_and_b32_e32 v59, 0xffff0000, v58
	v_lshlrev_b32_e32 v58, 16, v58
.Lpl_f44:
	v_pk_add_f32 v[140:141], v[140:141], v[58:59]
	v_pk_add_f32 v[142:143], v[142:143], v[60:61]
	v_pk_add_f32 v[144:145], v[144:145], v[62:63]
	v_pk_add_f32 v[146:147], v[146:147], v[64:65]
	s_waitcnt vmcnt(6)
	s_cmp_le_u32 4, s48
	s_cbranch_scc0 .Lpl_f45
	v_and_b32_e32 v221, 0xffff0000, v217
	v_lshlrev_b32_e32 v220, 16, v217
	v_and_b32_e32 v219, 0xffff0000, v216
	v_lshlrev_b32_e32 v218, 16, v216
	v_and_b32_e32 v217, 0xffff0000, v215
	v_lshlrev_b32_e32 v216, 16, v215
	v_and_b32_e32 v215, 0xffff0000, v214
	v_lshlrev_b32_e32 v214, 16, v214
.Lpl_f45:
	v_pk_add_f32 v[140:141], v[140:141], v[214:215]
	v_pk_add_f32 v[142:143], v[142:143], v[216:217]
	v_pk_add_f32 v[144:145], v[144:145], v[218:219]
	v_pk_add_f32 v[146:147], v[146:147], v[220:221]
	s_waitcnt vmcnt(4)
	s_cmp_le_u32 5, s48
	s_cbranch_scc0 .Lpl_f46
	v_and_b32_e32 v229, 0xffff0000, v225
	v_lshlrev_b32_e32 v228, 16, v225
	v_and_b32_e32 v227, 0xffff0000, v224
	v_lshlrev_b32_e32 v226, 16, v224
	v_and_b32_e32 v225, 0xffff0000, v223
	v_lshlrev_b32_e32 v224, 16, v223
	v_and_b32_e32 v223, 0xffff0000, v222
	v_lshlrev_b32_e32 v222, 16, v222
.Lpl_f46:
	v_pk_add_f32 v[140:141], v[140:141], v[222:223]
	v_pk_add_f32 v[142:143], v[142:143], v[224:225]
	v_pk_add_f32 v[144:145], v[144:145], v[226:227]
	v_pk_add_f32 v[146:147], v[146:147], v[228:229]
	s_waitcnt vmcnt(2)
	s_cmp_le_u32 6, s48
	s_cbranch_scc0 .Lpl_f47
	v_and_b32_e32 v237, 0xffff0000, v233
	v_lshlrev_b32_e32 v236, 16, v233
	v_and_b32_e32 v235, 0xffff0000, v232
	v_lshlrev_b32_e32 v234, 16, v232
	v_and_b32_e32 v233, 0xffff0000, v231
	v_lshlrev_b32_e32 v232, 16, v231
	v_and_b32_e32 v231, 0xffff0000, v230
	v_lshlrev_b32_e32 v230, 16, v230
.Lpl_f47:
	v_pk_add_f32 v[140:141], v[140:141], v[230:231]
	v_pk_add_f32 v[142:143], v[142:143], v[232:233]
	v_pk_add_f32 v[144:145], v[144:145], v[234:235]
	v_pk_add_f32 v[146:147], v[146:147], v[236:237]
	s_waitcnt vmcnt(0)
	s_cmp_le_u32 7, s48
	s_cbranch_scc0 .Lpl_f48
	v_and_b32_e32 v245, 0xffff0000, v241
	v_lshlrev_b32_e32 v244, 16, v241
	v_and_b32_e32 v243, 0xffff0000, v240
	v_lshlrev_b32_e32 v242, 16, v240
	v_and_b32_e32 v241, 0xffff0000, v239
	v_lshlrev_b32_e32 v240, 16, v239
	v_and_b32_e32 v239, 0xffff0000, v238
	v_lshlrev_b32_e32 v238, 16, v238

.Lpl_w4:
	s_cmp_le_u32 0, s48
	s_cselect_b64 s[6:7], s[20:21], s[82:83]
	s_cselect_b64 vcc, -1, 0
	v_cndmask_b32_e32 v136, v135, v161, vcc
	global_load_dwordx4 v[34:37], v136, s[6:7]
	global_load_dwordx4 v[38:41], v136, s[6:7] offset:16
	s_cmp_le_u32 1, s48
	s_cselect_b64 s[6:7], s[20:21], s[82:83]
	s_cselect_b64 vcc, -1, 0
	v_subrev_u32_e32 v136, 0x800, v161
	v_subrev_u32_e32 v137, 0x1000, v135
	v_cndmask_b32_e32 v136, v137, v136, vcc
	global_load_dwordx4 v[42:45], v136, s[6:7]
	global_load_dwordx4 v[46:49], v136, s[6:7] offset:16
	s_cmp_le_u32 2, s48
	s_cselect_b64 s[6:7], s[20:21], s[82:83]
	s_cselect_b64 vcc, -1, 0
	v_subrev_u32_e32 v136, 0x1000, v161
	v_subrev_u32_e32 v137, 0x2000, v135
	v_cndmask_b32_e32 v136, v137, v136, vcc
	global_load_dwordx4 v[50:53], v136, s[6:7]
	global_load_dwordx4 v[54:57], v136, s[6:7] offset:16
	s_cmp_le_u32 3, s48
	s_cselect_b64 s[6:7], s[20:21], s[82:83]
	s_cselect_b64 vcc, -1, 0
	v_subrev_u32_e32 v136, 0x1800, v161
	v_subrev_u32_e32 v137, 0x3000, v135
	v_cndmask_b32_e32 v136, v137, v136, vcc
	global_load_dwordx4 v[58:61], v136, s[6:7]
	global_load_dwordx4 v[62:65], v136, s[6:7] offset:16
	v_add_u32_e32 v161, 0x8000, v161
	v_add_u32_e32 v135, 0x1e000, v135
	s_cmp_le_u32 0, s48
	s_cselect_b64 s[6:7], s[20:21], s[82:83]
	s_cselect_b64 vcc, -1, 0
	v_cndmask_b32_e32 v136, v135, v161, vcc
	global_load_dwordx4 v[214:217], v136, s[6:7]
	global_load_dwordx4 v[218:221], v136, s[6:7] offset:16
	s_cmp_le_u32 1, s48
	s_cselect_b64 s[6:7], s[20:21], s[82:83]
	s_cselect_b64 vcc, -1, 0
	v_subrev_u32_e32 v136, 0x800, v161
	v_subrev_u32_e32 v137, 0x1000, v135
	v_cndmask_b32_e32 v136, v137, v136, vcc
	global_load_dwordx4 v[222:225], v136, s[6:7]
	global_load_dwordx4 v[226:229], v136, s[6:7] offset:16
	s_cmp_le_u32 2, s48
	s_cselect_b64 s[6:7], s[20:21], s[82:83]
	s_cselect_b64 vcc, -1, 0
	v_subrev_u32_e32 v136, 0x1000, v161
	v_subrev_u32_e32 v137, 0x2000, v135
	v_cndmask_b32_e32 v136, v137, v136, vcc
	global_load_dwordx4 v[230:233], v136, s[6:7]
	global_load_dwordx4 v[234:237], v136, s[6:7] offset:16
	s_cmp_le_u32 3, s48
	s_cselect_b64 s[6:7], s[20:21], s[82:83]
	s_cselect_b64 vcc, -1, 0
	v_subrev_u32_e32 v136, 0x1800, v161
	v_subrev_u32_e32 v137, 0x3000, v135
	v_cndmask_b32_e32 v136, v137, v136, vcc
	global_load_dwordx4 v[238:241], v136, s[6:7]
	global_load_dwordx4 v[242:245], v136, s[6:7] offset:16
	s_mov_b32 s47, 3

.Lpl_f52:
	v_pk_add_f32 v[140:141], v[140:141], v[58:59]
	v_pk_add_f32 v[142:143], v[142:143], v[60:61]
	v_pk_add_f32 v[144:145], v[144:145], v[62:63]
	v_pk_add_f32 v[146:147], v[146:147], v[64:65]
	v_pk_fma_f32 v[140:141], v[98:99], v[140:141], v[148:149] neg_lo:[0,0,1] neg_hi:[0,0,1]
	v_pk_fma_f32 v[142:143], v[98:99], v[142:143], v[150:151] neg_lo:[0,0,1] neg_hi:[0,0,1]
	v_pk_fma_f32 v[144:145], v[98:99], v[144:145], v[152:153] neg_lo:[0,0,1] neg_hi:[0,0,1]
	v_pk_fma_f32 v[146:147], v[98:99], v[146:147], v[154:155] neg_lo:[0,0,1] neg_hi:[0,0,1]
	v_cvt_pk_bf16_f32 v156, v140, v141
	v_cvt_pk_bf16_f32 v157, v142, v143
	v_cvt_pk_bf16_f32 v158, v144, v145
	v_cvt_pk_bf16_f32 v159, v146, v147
	ds_write_b128 v160, v[156:159]
	v_add_u32_e32 v160, 0x2100, v160
	s_cmp_le_u32 3, s48
	s_cselect_b64 s[6:7], s[20:21], s[82:83]
	s_cselect_b64 vcc, -1, 0
	v_subrev_u32_e32 v136, 0x1800, v161
	v_subrev_u32_e32 v137, 0x3000, v135
	v_cndmask_b32_e32 v136, v137, v136, vcc
	global_load_dwordx4 v[58:61], v136, s[6:7]
	global_load_dwordx4 v[62:65], v136, s[6:7] offset:16
	s_waitcnt vmcnt(14)
	s_cmp_le_u32 0, s48
	s_cbranch_scc0 .Lpl_f53
	v_and_b32_e32 v221, 0xffff0000, v217
	v_lshlrev_b32_e32 v220, 16, v217
	v_and_b32_e32 v219, 0xffff0000, v216
	v_lshlrev_b32_e32 v218, 16, v216
	v_and_b32_e32 v217, 0xffff0000, v215
	v_lshlrev_b32_e32 v216, 16, v215
	v_and_b32_e32 v215, 0xffff0000, v214
	v_lshlrev_b32_e32 v214, 16, v214
.Lpl_f53:
	v_mov_b64_e32 v[148:149], v[214:215]
	v_mov_b64_e32 v[150:151], v[216:217]
	v_mov_b64_e32 v[152:153], v[218:219]
	v_mov_b64_e32 v[154:155], v[220:221]
	v_pk_add_f32 v[140:141], v[214:215], 0
	v_pk_add_f32 v[142:143], v[216:217], 0
	v_pk_add_f32 v[144:145], v[218:219], 0
	v_pk_add_f32 v[146:147], v[220:221], 0
	v_add_u32_e32 v161, 0x8000, v161
	v_add_u32_e32 v135, 0x1e000, v135
	s_cmp_le_u32 0, s48
	s_cselect_b64 s[6:7], s[20:21], s[82:83]
	s_cselect_b64 vcc, -1, 0
	v_cndmask_b32_e32 v136, v135, v161, vcc
	global_load_dwordx4 v[214:217], v136, s[6:7]
	global_load_dwordx4 v[218:221], v136, s[6:7] offset:16
	s_waitcnt vmcnt(14)
	s_cmp_le_u32 1, s48
	s_cbranch_scc0 .Lpl_f54
	v_and_b32_e32 v229, 0xffff0000, v225
	v_lshlrev_b32_e32 v228, 16, v225
	v_and_b32_e32 v227, 0xffff0000, v224
	v_lshlrev_b32_e32 v226, 16, v224
	v_and_b32_e32 v225, 0xffff0000, v223
	v_lshlrev_b32_e32 v224, 16, v223
	v_and_b32_e32 v223, 0xffff0000, v222
	v_lshlrev_b32_e32 v222, 16, v222
.Lpl_f54:
	v_pk_add_f32 v[140:141], v[140:141], v[222:223]
	v_pk_add_f32 v[142:143], v[142:143], v[224:225]
	v_pk_add_f32 v[144:145], v[144:145], v[226:227]
	v_pk_add_f32 v[146:147], v[146:147], v[228:229]
	s_cmp_le_u32 1, s48
	s_cselect_b64 s[6:7], s[20:21], s[82:83]
	s_cselect_b64 vcc, -1, 0
	v_subrev_u32_e32 v136, 0x800, v161
	v_subrev_u32_e32 v137, 0x1000, v135
	v_cndmask_b32_e32 v136, v137, v136, vcc
	global_load_dwordx4 v[222:225], v136, s[6:7]
	global_load_dwordx4 v[226:229], v136, s[6:7] offset:16
	s_waitcnt vmcnt(14)
	s_cmp_le_u32 2, s48
	s_cbranch_scc0 .Lpl_f55
	v_and_b32_e32 v237, 0xffff0000, v233
	v_lshlrev_b32_e32 v236, 16, v233
	v_and_b32_e32 v235, 0xffff0000, v232
	v_lshlrev_b32_e32 v234, 16, v232
	v_and_b32_e32 v233, 0xffff0000, v231
	v_lshlrev_b32_e32 v232, 16, v231
	v_and_b32_e32 v231, 0xffff0000, v230
	v_lshlrev_b32_e32 v230, 16, v230
.Lpl_f55:
	v_pk_add_f32 v[140:141], v[140:141], v[230:231]
	v_pk_add_f32 v[142:143], v[142:143], v[232:233]
	v_pk_add_f32 v[144:145], v[144:145], v[234:235]
	v_pk_add_f32 v[146:147], v[146:147], v[236:237]
	s_cmp_le_u32 2, s48
	s_cselect_b64 s[6:7], s[20:21], s[82:83]
	s_cselect_b64 vcc, -1, 0
	v_subrev_u32_e32 v136, 0x1000, v161
	v_subrev_u32_e32 v137, 0x2000, v135
	v_cndmask_b32_e32 v136, v137, v136, vcc
	global_load_dwordx4 v[230:233], v136, s[6:7]
	global_load_dwordx4 v[234:237], v136, s[6:7] offset:16
	s_waitcnt vmcnt(14)
	s_cmp_le_u32 3, s48
	s_cbranch_scc0 .Lpl_f56
	v_and_b32_e32 v245, 0xffff0000, v241
	v_lshlrev_b32_e32 v244, 16, v241
	v_and_b32_e32 v243, 0xffff0000, v240
	v_lshlrev_b32_e32 v242, 16, v240
	v_and_b32_e32 v241, 0xffff0000, v239
	v_lshlrev_b32_e32 v240, 16, v239
	v_and_b32_e32 v239, 0xffff0000, v238
	v_lshlrev_b32_e32 v238, 16, v238
.Lpl_f56:
	v_pk_add_f32 v[140:141], v[140:141], v[238:239]
	v_pk_add_f32 v[142:143], v[142:143], v[240:241]
	v_pk_add_f32 v[144:145], v[144:145], v[242:243]
	v_pk_add_f32 v[146:147], v[146:147], v[244:245]
	v_pk_fma_f32 v[140:141], v[98:99], v[140:141], v[148:149] neg_lo:[0,0,1] neg_hi:[0,0,1]
	v_pk_fma_f32 v[142:143], v[98:99], v[142:143], v[150:151] neg_lo:[0,0,1] neg_hi:[0,0,1]
	v_pk_fma_f32 v[144:145], v[98:99], v[144:145], v[152:153] neg_lo:[0,0,1] neg_hi:[0,0,1]
	v_pk_fma_f32 v[146:147], v[98:99], v[146:147], v[154:155] neg_lo:[0,0,1] neg_hi:[0,0,1]
	v_cvt_pk_bf16_f32 v156, v140, v141
	v_cvt_pk_bf16_f32 v157, v142, v143
	v_cvt_pk_bf16_f32 v158, v144, v145
	v_cvt_pk_bf16_f32 v159, v146, v147
	ds_write_b128 v160, v[156:159]
	v_add_u32_e32 v160, 0x2100, v160
	s_cmp_le_u32 3, s48
	s_cselect_b64 s[6:7], s[20:21], s[82:83]
	s_cselect_b64 vcc, -1, 0
	v_subrev_u32_e32 v136, 0x1800, v161
	v_subrev_u32_e32 v137, 0x3000, v135
	v_cndmask_b32_e32 v136, v137, v136, vcc
	global_load_dwordx4 v[238:241], v136, s[6:7]
	global_load_dwordx4 v[242:245], v136, s[6:7] offset:16
	s_add_i32 s47, s47, -1
	s_cmp_lg_u32 s47, 0
	s_cbranch_scc1 .Lpl_w4_loop
	s_waitcnt vmcnt(14)
	s_cmp_le_u32 0, s48
	s_cbranch_scc0 .Lpl_f57
	v_and_b32_e32 v41, 0xffff0000, v37
	v_lshlrev_b32_e32 v40, 16, v37
	v_and_b32_e32 v39, 0xffff0000, v36
	v_lshlrev_b32_e32 v38, 16, v36
	v_and_b32_e32 v37, 0xffff0000, v35
	v_lshlrev_b32_e32 v36, 16, v35
	v_and_b32_e32 v35, 0xffff0000, v34
	v_lshlrev_b32_e32 v34, 16, v34

.Lpl_f60:
	v_pk_add_f32 v[140:141], v[140:141], v[58:59]
	v_pk_add_f32 v[142:143], v[142:143], v[60:61]
	v_pk_add_f32 v[144:145], v[144:145], v[62:63]
	v_pk_add_f32 v[146:147], v[146:147], v[64:65]
	v_pk_fma_f32 v[140:141], v[98:99], v[140:141], v[148:149] neg_lo:[0,0,1] neg_hi:[0,0,1]
	v_pk_fma_f32 v[142:143], v[98:99], v[142:143], v[150:151] neg_lo:[0,0,1] neg_hi:[0,0,1]
	v_pk_fma_f32 v[144:145], v[98:99], v[144:145], v[152:153] neg_lo:[0,0,1] neg_hi:[0,0,1]
	v_pk_fma_f32 v[146:147], v[98:99], v[146:147], v[154:155] neg_lo:[0,0,1] neg_hi:[0,0,1]
	v_cvt_pk_bf16_f32 v156, v140, v141
	v_cvt_pk_bf16_f32 v157, v142, v143
	v_cvt_pk_bf16_f32 v158, v144, v145
	v_cvt_pk_bf16_f32 v159, v146, v147
	ds_write_b128 v160, v[156:159]
	v_add_u32_e32 v160, 0x2100, v160
	s_waitcnt vmcnt(6)
	s_cmp_le_u32 0, s48
	s_cbranch_scc0 .Lpl_f61
	v_and_b32_e32 v221, 0xffff0000, v217
	v_lshlrev_b32_e32 v220, 16, v217
	v_and_b32_e32 v219, 0xffff0000, v216
	v_lshlrev_b32_e32 v218, 16, v216
	v_and_b32_e32 v217, 0xffff0000, v215
	v_lshlrev_b32_e32 v216, 16, v215
	v_and_b32_e32 v215, 0xffff0000, v214
	v_lshlrev_b32_e32 v214, 16, v214
.Lpl_f61:
	v_mov_b64_e32 v[148:149], v[214:215]
	v_mov_b64_e32 v[150:151], v[216:217]
	v_mov_b64_e32 v[152:153], v[218:219]
	v_mov_b64_e32 v[154:155], v[220:221]
	v_pk_add_f32 v[140:141], v[214:215], 0
	v_pk_add_f32 v[142:143], v[216:217], 0
	v_pk_add_f32 v[144:145], v[218:219], 0
	v_pk_add_f32 v[146:147], v[220:221], 0
	s_waitcnt vmcnt(4)
	s_cmp_le_u32 1, s48
	s_cbranch_scc0 .Lpl_f62
	v_and_b32_e32 v229, 0xffff0000, v225
	v_lshlrev_b32_e32 v228, 16, v225
	v_and_b32_e32 v227, 0xffff0000, v224
	v_lshlrev_b32_e32 v226, 16, v224
	v_and_b32_e32 v225, 0xffff0000, v223
	v_lshlrev_b32_e32 v224, 16, v223
	v_and_b32_e32 v223, 0xffff0000, v222
	v_lshlrev_b32_e32 v222, 16, v222
.Lpl_f62:
	v_pk_add_f32 v[140:141], v[140:141], v[222:223]
	v_pk_add_f32 v[142:143], v[142:143], v[224:225]
	v_pk_add_f32 v[144:145], v[144:145], v[226:227]
	v_pk_add_f32 v[146:147], v[146:147], v[228:229]
	s_waitcnt vmcnt(2)
	s_cmp_le_u32 2, s48
	s_cbranch_scc0 .Lpl_f63
	v_and_b32_e32 v237, 0xffff0000, v233
	v_lshlrev_b32_e32 v236, 16, v233
	v_and_b32_e32 v235, 0xffff0000, v232
	v_lshlrev_b32_e32 v234, 16, v232
	v_and_b32_e32 v233, 0xffff0000, v231
	v_lshlrev_b32_e32 v232, 16, v231
	v_and_b32_e32 v231, 0xffff0000, v230
	v_lshlrev_b32_e32 v230, 16, v230
.Lpl_f63:
	v_pk_add_f32 v[140:141], v[140:141], v[230:231]
	v_pk_add_f32 v[142:143], v[142:143], v[232:233]
	v_pk_add_f32 v[144:145], v[144:145], v[234:235]
	v_pk_add_f32 v[146:147], v[146:147], v[236:237]
	s_waitcnt vmcnt(0)
	s_cmp_le_u32 3, s48
	s_cbranch_scc0 .Lpl_f64
	v_and_b32_e32 v245, 0xffff0000, v241
	v_lshlrev_b32_e32 v244, 16, v241
	v_and_b32_e32 v243, 0xffff0000, v240
	v_lshlrev_b32_e32 v242, 16, v240
	v_and_b32_e32 v241, 0xffff0000, v239
	v_lshlrev_b32_e32 v240, 16, v239
	v_and_b32_e32 v239, 0xffff0000, v238
	v_lshlrev_b32_e32 v238, 16, v238

.Lpl_w2:
	s_cmp_le_u32 0, s48
	s_cselect_b64 s[6:7], s[20:21], s[82:83]
	s_cselect_b64 vcc, -1, 0
	v_cndmask_b32_e32 v136, v135, v161, vcc
	global_load_dwordx4 v[34:37], v136, s[6:7]
	global_load_dwordx4 v[38:41], v136, s[6:7] offset:16
	s_cmp_le_u32 1, s48
	s_cselect_b64 s[6:7], s[20:21], s[82:83]
	s_cselect_b64 vcc, -1, 0
	v_subrev_u32_e32 v136, 0x800, v161
	v_subrev_u32_e32 v137, 0x1000, v135
	v_cndmask_b32_e32 v136, v137, v136, vcc
	global_load_dwordx4 v[42:45], v136, s[6:7]
	global_load_dwordx4 v[46:49], v136, s[6:7] offset:16
	v_add_u32_e32 v161, 0x8000, v161
	v_add_u32_e32 v135, 0x1e000, v135
	s_cmp_le_u32 0, s48
	s_cselect_b64 s[6:7], s[20:21], s[82:83]
	s_cselect_b64 vcc, -1, 0
	v_cndmask_b32_e32 v136, v135, v161, vcc
	global_load_dwordx4 v[50:53], v136, s[6:7]
	global_load_dwordx4 v[54:57], v136, s[6:7] offset:16
	s_cmp_le_u32 1, s48
	s_cselect_b64 s[6:7], s[20:21], s[82:83]
	s_cselect_b64 vcc, -1, 0
	v_subrev_u32_e32 v136, 0x800, v161
	v_subrev_u32_e32 v137, 0x1000, v135
	v_cndmask_b32_e32 v136, v137, v136, vcc
	global_load_dwordx4 v[58:61], v136, s[6:7]
	global_load_dwordx4 v[62:65], v136, s[6:7] offset:16
	v_add_u32_e32 v161, 0x8000, v161
	v_add_u32_e32 v135, 0x1e000, v135
	s_cmp_le_u32 0, s48
	s_cselect_b64 s[6:7], s[20:21], s[82:83]
	s_cselect_b64 vcc, -1, 0
	v_cndmask_b32_e32 v136, v135, v161, vcc
	global_load_dwordx4 v[214:217], v136, s[6:7]
	global_load_dwordx4 v[218:221], v136, s[6:7] offset:16
	s_cmp_le_u32 1, s48
	s_cselect_b64 s[6:7], s[20:21], s[82:83]
	s_cselect_b64 vcc, -1, 0
	v_subrev_u32_e32 v136, 0x800, v161
	v_subrev_u32_e32 v137, 0x1000, v135
	v_cndmask_b32_e32 v136, v137, v136, vcc
	global_load_dwordx4 v[222:225], v136, s[6:7]
	global_load_dwordx4 v[226:229], v136, s[6:7] offset:16
	v_add_u32_e32 v161, 0x8000, v161
	v_add_u32_e32 v135, 0x1e000, v135
	s_cmp_le_u32 0, s48
	s_cselect_b64 s[6:7], s[20:21], s[82:83]
	s_cselect_b64 vcc, -1, 0
	v_cndmask_b32_e32 v136, v135, v161, vcc
	global_load_dwordx4 v[230:233], v136, s[6:7]
	global_load_dwordx4 v[234:237], v136, s[6:7] offset:16
	s_cmp_le_u32 1, s48
	s_cselect_b64 s[6:7], s[20:21], s[82:83]
	s_cselect_b64 vcc, -1, 0
	v_subrev_u32_e32 v136, 0x800, v161
	v_subrev_u32_e32 v137, 0x1000, v135
	v_cndmask_b32_e32 v136, v137, v136, vcc
	global_load_dwordx4 v[238:241], v136, s[6:7]
	global_load_dwordx4 v[242:245], v136, s[6:7] offset:16
	s_mov_b32 s47, 1

.Lpl_f66:
	v_pk_add_f32 v[140:141], v[140:141], v[42:43]
	v_pk_add_f32 v[142:143], v[142:143], v[44:45]
	v_pk_add_f32 v[144:145], v[144:145], v[46:47]
	v_pk_add_f32 v[146:147], v[146:147], v[48:49]
	v_pk_fma_f32 v[140:141], v[98:99], v[140:141], v[148:149] neg_lo:[0,0,1] neg_hi:[0,0,1]
	v_pk_fma_f32 v[142:143], v[98:99], v[142:143], v[150:151] neg_lo:[0,0,1] neg_hi:[0,0,1]
	v_pk_fma_f32 v[144:145], v[98:99], v[144:145], v[152:153] neg_lo:[0,0,1] neg_hi:[0,0,1]
	v_pk_fma_f32 v[146:147], v[98:99], v[146:147], v[154:155] neg_lo:[0,0,1] neg_hi:[0,0,1]
	v_cvt_pk_bf16_f32 v156, v140, v141
	v_cvt_pk_bf16_f32 v157, v142, v143
	v_cvt_pk_bf16_f32 v158, v144, v145
	v_cvt_pk_bf16_f32 v159, v146, v147
	ds_write_b128 v160, v[156:159]
	v_add_u32_e32 v160, 0x2100, v160
	s_cmp_le_u32 1, s48
	s_cselect_b64 s[6:7], s[20:21], s[82:83]
	s_cselect_b64 vcc, -1, 0
	v_subrev_u32_e32 v136, 0x800, v161
	v_subrev_u32_e32 v137, 0x1000, v135
	v_cndmask_b32_e32 v136, v137, v136, vcc
	global_load_dwordx4 v[42:45], v136, s[6:7]
	global_load_dwordx4 v[46:49], v136, s[6:7] offset:16
	s_waitcnt vmcnt(14)
	s_cmp_le_u32 0, s48
	s_cbranch_scc0 .Lpl_f67
	v_and_b32_e32 v57, 0xffff0000, v53
	v_lshlrev_b32_e32 v56, 16, v53
	v_and_b32_e32 v55, 0xffff0000, v52
	v_lshlrev_b32_e32 v54, 16, v52
	v_and_b32_e32 v53, 0xffff0000, v51
	v_lshlrev_b32_e32 v52, 16, v51
	v_and_b32_e32 v51, 0xffff0000, v50
	v_lshlrev_b32_e32 v50, 16, v50
.Lpl_f67:
	v_mov_b64_e32 v[148:149], v[50:51]
	v_mov_b64_e32 v[150:151], v[52:53]
	v_mov_b64_e32 v[152:153], v[54:55]
	v_mov_b64_e32 v[154:155], v[56:57]
	v_pk_add_f32 v[140:141], v[50:51], 0
	v_pk_add_f32 v[142:143], v[52:53], 0
	v_pk_add_f32 v[144:145], v[54:55], 0
	v_pk_add_f32 v[146:147], v[56:57], 0
	v_add_u32_e32 v161, 0x8000, v161
	v_add_u32_e32 v135, 0x1e000, v135
	s_cmp_le_u32 0, s48
	s_cselect_b64 s[6:7], s[20:21], s[82:83]
	s_cselect_b64 vcc, -1, 0
	v_cndmask_b32_e32 v136, v135, v161, vcc
	global_load_dwordx4 v[50:53], v136, s[6:7]
	global_load_dwordx4 v[54:57], v136, s[6:7] offset:16
	s_waitcnt vmcnt(14)
	s_cmp_le_u32 1, s48
	s_cbranch_scc0 .Lpl_f68
	v_and_b32_e32 v65, 0xffff0000, v61
	v_lshlrev_b32_e32 v64, 16, v61
	v_and_b32_e32 v63, 0xffff0000, v60
	v_lshlrev_b32_e32 v62, 16, v60
	v_and_b32_e32 v61, 0xffff0000, v59
	v_lshlrev_b32_e32 v60, 16, v59
	v_and_b32_e32 v59, 0xffff0000, v58
	v_lshlrev_b32_e32 v58, 16, v58
.Lpl_f68:
	v_pk_add_f32 v[140:141], v[140:141], v[58:59]
	v_pk_add_f32 v[142:143], v[142:143], v[60:61]
	v_pk_add_f32 v[144:145], v[144:145], v[62:63]
	v_pk_add_f32 v[146:147], v[146:147], v[64:65]
	v_pk_fma_f32 v[140:141], v[98:99], v[140:141], v[148:149] neg_lo:[0,0,1] neg_hi:[0,0,1]
	v_pk_fma_f32 v[142:143], v[98:99], v[142:143], v[150:151] neg_lo:[0,0,1] neg_hi:[0,0,1]
	v_pk_fma_f32 v[144:145], v[98:99], v[144:145], v[152:153] neg_lo:[0,0,1] neg_hi:[0,0,1]
	v_pk_fma_f32 v[146:147], v[98:99], v[146:147], v[154:155] neg_lo:[0,0,1] neg_hi:[0,0,1]
	v_cvt_pk_bf16_f32 v156, v140, v141
	v_cvt_pk_bf16_f32 v157, v142, v143
	v_cvt_pk_bf16_f32 v158, v144, v145
	v_cvt_pk_bf16_f32 v159, v146, v147
	ds_write_b128 v160, v[156:159]
	v_add_u32_e32 v160, 0x2100, v160
	s_cmp_le_u32 1, s48
	s_cselect_b64 s[6:7], s[20:21], s[82:83]
	s_cselect_b64 vcc, -1, 0
	v_subrev_u32_e32 v136, 0x800, v161
	v_subrev_u32_e32 v137, 0x1000, v135
	v_cndmask_b32_e32 v136, v137, v136, vcc
	global_load_dwordx4 v[58:61], v136, s[6:7]
	global_load_dwordx4 v[62:65], v136, s[6:7] offset:16
	s_waitcnt vmcnt(14)
	s_cmp_le_u32 0, s48
	s_cbranch_scc0 .Lpl_f69
	v_and_b32_e32 v221, 0xffff0000, v217
	v_lshlrev_b32_e32 v220, 16, v217
	v_and_b32_e32 v219, 0xffff0000, v216
	v_lshlrev_b32_e32 v218, 16, v216
	v_and_b32_e32 v217, 0xffff0000, v215
	v_lshlrev_b32_e32 v216, 16, v215
	v_and_b32_e32 v215, 0xffff0000, v214
	v_lshlrev_b32_e32 v214, 16, v214

.Lpl_f70:
	v_pk_add_f32 v[140:141], v[140:141], v[222:223]
	v_pk_add_f32 v[142:143], v[142:143], v[224:225]
	v_pk_add_f32 v[144:145], v[144:145], v[226:227]
	v_pk_add_f32 v[146:147], v[146:147], v[228:229]
	v_pk_fma_f32 v[140:141], v[98:99], v[140:141], v[148:149] neg_lo:[0,0,1] neg_hi:[0,0,1]
	v_pk_fma_f32 v[142:143], v[98:99], v[142:143], v[150:151] neg_lo:[0,0,1] neg_hi:[0,0,1]
	v_pk_fma_f32 v[144:145], v[98:99], v[144:145], v[152:153] neg_lo:[0,0,1] neg_hi:[0,0,1]
	v_pk_fma_f32 v[146:147], v[98:99], v[146:147], v[154:155] neg_lo:[0,0,1] neg_hi:[0,0,1]
	v_cvt_pk_bf16_f32 v156, v140, v141
	v_cvt_pk_bf16_f32 v157, v142, v143
	v_cvt_pk_bf16_f32 v158, v144, v145
	v_cvt_pk_bf16_f32 v159, v146, v147
	ds_write_b128 v160, v[156:159]
	v_add_u32_e32 v160, 0x2100, v160
	s_cmp_le_u32 1, s48
	s_cselect_b64 s[6:7], s[20:21], s[82:83]
	s_cselect_b64 vcc, -1, 0
	v_subrev_u32_e32 v136, 0x800, v161
	v_subrev_u32_e32 v137, 0x1000, v135
	v_cndmask_b32_e32 v136, v137, v136, vcc
	global_load_dwordx4 v[222:225], v136, s[6:7]
	global_load_dwordx4 v[226:229], v136, s[6:7] offset:16
	s_waitcnt vmcnt(14)
	s_cmp_le_u32 0, s48
	s_cbranch_scc0 .Lpl_f71
	v_and_b32_e32 v237, 0xffff0000, v233
	v_lshlrev_b32_e32 v236, 16, v233
	v_and_b32_e32 v235, 0xffff0000, v232
	v_lshlrev_b32_e32 v234, 16, v232
	v_and_b32_e32 v233, 0xffff0000, v231
	v_lshlrev_b32_e32 v232, 16, v231
	v_and_b32_e32 v231, 0xffff0000, v230
	v_lshlrev_b32_e32 v230, 16, v230
.Lpl_f71:
	v_mov_b64_e32 v[148:149], v[230:231]
	v_mov_b64_e32 v[150:151], v[232:233]
	v_mov_b64_e32 v[152:153], v[234:235]
	v_mov_b64_e32 v[154:155], v[236:237]
	v_pk_add_f32 v[140:141], v[230:231], 0
	v_pk_add_f32 v[142:143], v[232:233], 0
	v_pk_add_f32 v[144:145], v[234:235], 0
	v_pk_add_f32 v[146:147], v[236:237], 0
	v_add_u32_e32 v161, 0x8000, v161
	v_add_u32_e32 v135, 0x1e000, v135
	s_cmp_le_u32 0, s48
	s_cselect_b64 s[6:7], s[20:21], s[82:83]
	s_cselect_b64 vcc, -1, 0
	v_cndmask_b32_e32 v136, v135, v161, vcc
	global_load_dwordx4 v[230:233], v136, s[6:7]
	global_load_dwordx4 v[234:237], v136, s[6:7] offset:16
	s_waitcnt vmcnt(14)
	s_cmp_le_u32 1, s48
	s_cbranch_scc0 .Lpl_f72
	v_and_b32_e32 v245, 0xffff0000, v241
	v_lshlrev_b32_e32 v244, 16, v241
	v_and_b32_e32 v243, 0xffff0000, v240
	v_lshlrev_b32_e32 v242, 16, v240
	v_and_b32_e32 v241, 0xffff0000, v239
	v_lshlrev_b32_e32 v240, 16, v239
	v_and_b32_e32 v239, 0xffff0000, v238
	v_lshlrev_b32_e32 v238, 16, v238
.Lpl_f72:
	v_pk_add_f32 v[140:141], v[140:141], v[238:239]
	v_pk_add_f32 v[142:143], v[142:143], v[240:241]
	v_pk_add_f32 v[144:145], v[144:145], v[242:243]
	v_pk_add_f32 v[146:147], v[146:147], v[244:245]
	v_pk_fma_f32 v[140:141], v[98:99], v[140:141], v[148:149] neg_lo:[0,0,1] neg_hi:[0,0,1]
	v_pk_fma_f32 v[142:143], v[98:99], v[142:143], v[150:151] neg_lo:[0,0,1] neg_hi:[0,0,1]
	v_pk_fma_f32 v[144:145], v[98:99], v[144:145], v[152:153] neg_lo:[0,0,1] neg_hi:[0,0,1]
	v_pk_fma_f32 v[146:147], v[98:99], v[146:147], v[154:155] neg_lo:[0,0,1] neg_hi:[0,0,1]
	v_cvt_pk_bf16_f32 v156, v140, v141
	v_cvt_pk_bf16_f32 v157, v142, v143
	v_cvt_pk_bf16_f32 v158, v144, v145
	v_cvt_pk_bf16_f32 v159, v146, v147
	ds_write_b128 v160, v[156:159]
	v_add_u32_e32 v160, 0x2100, v160
	s_cmp_le_u32 1, s48
	s_cselect_b64 s[6:7], s[20:21], s[82:83]
	s_cselect_b64 vcc, -1, 0
	v_subrev_u32_e32 v136, 0x800, v161
	v_subrev_u32_e32 v137, 0x1000, v135
	v_cndmask_b32_e32 v136, v137, v136, vcc
	global_load_dwordx4 v[238:241], v136, s[6:7]
	global_load_dwordx4 v[242:245], v136, s[6:7] offset:16
	s_add_i32 s47, s47, -1
	s_cmp_lg_u32 s47, 0
	s_cbranch_scc1 .Lpl_w2_loop
	s_waitcnt vmcnt(14)
	s_cmp_le_u32 0, s48
	s_cbranch_scc0 .Lpl_f73
	v_and_b32_e32 v41, 0xffff0000, v37
	v_lshlrev_b32_e32 v40, 16, v37
	v_and_b32_e32 v39, 0xffff0000, v36
	v_lshlrev_b32_e32 v38, 16, v36
	v_and_b32_e32 v37, 0xffff0000, v35
	v_lshlrev_b32_e32 v36, 16, v35
	v_and_b32_e32 v35, 0xffff0000, v34
	v_lshlrev_b32_e32 v34, 16, v34

.Lpl_f74:
	v_pk_add_f32 v[140:141], v[140:141], v[42:43]
	v_pk_add_f32 v[142:143], v[142:143], v[44:45]
	v_pk_add_f32 v[144:145], v[144:145], v[46:47]
	v_pk_add_f32 v[146:147], v[146:147], v[48:49]
	v_pk_fma_f32 v[140:141], v[98:99], v[140:141], v[148:149] neg_lo:[0,0,1] neg_hi:[0,0,1]
	v_pk_fma_f32 v[142:143], v[98:99], v[142:143], v[150:151] neg_lo:[0,0,1] neg_hi:[0,0,1]
	v_pk_fma_f32 v[144:145], v[98:99], v[144:145], v[152:153] neg_lo:[0,0,1] neg_hi:[0,0,1]
	v_pk_fma_f32 v[146:147], v[98:99], v[146:147], v[154:155] neg_lo:[0,0,1] neg_hi:[0,0,1]
	v_cvt_pk_bf16_f32 v156, v140, v141
	v_cvt_pk_bf16_f32 v157, v142, v143
	v_cvt_pk_bf16_f32 v158, v144, v145
	v_cvt_pk_bf16_f32 v159, v146, v147
	ds_write_b128 v160, v[156:159]
	v_add_u32_e32 v160, 0x2100, v160
	s_waitcnt vmcnt(10)
	s_cmp_le_u32 0, s48
	s_cbranch_scc0 .Lpl_f75
	v_and_b32_e32 v57, 0xffff0000, v53
	v_lshlrev_b32_e32 v56, 16, v53
	v_and_b32_e32 v55, 0xffff0000, v52
	v_lshlrev_b32_e32 v54, 16, v52
	v_and_b32_e32 v53, 0xffff0000, v51
	v_lshlrev_b32_e32 v52, 16, v51
	v_and_b32_e32 v51, 0xffff0000, v50
	v_lshlrev_b32_e32 v50, 16, v50
.Lpl_f75:
	v_mov_b64_e32 v[148:149], v[50:51]
	v_mov_b64_e32 v[150:151], v[52:53]
	v_mov_b64_e32 v[152:153], v[54:55]
	v_mov_b64_e32 v[154:155], v[56:57]
	v_pk_add_f32 v[140:141], v[50:51], 0
	v_pk_add_f32 v[142:143], v[52:53], 0
	v_pk_add_f32 v[144:145], v[54:55], 0
	v_pk_add_f32 v[146:147], v[56:57], 0
	s_waitcnt vmcnt(8)
	s_cmp_le_u32 1, s48
	s_cbranch_scc0 .Lpl_f76
	v_and_b32_e32 v65, 0xffff0000, v61
	v_lshlrev_b32_e32 v64, 16, v61
	v_and_b32_e32 v63, 0xffff0000, v60
	v_lshlrev_b32_e32 v62, 16, v60
	v_and_b32_e32 v61, 0xffff0000, v59
	v_lshlrev_b32_e32 v60, 16, v59
	v_and_b32_e32 v59, 0xffff0000, v58
	v_lshlrev_b32_e32 v58, 16, v58

.Lpl_f78:
	v_pk_add_f32 v[140:141], v[140:141], v[222:223]
	v_pk_add_f32 v[142:143], v[142:143], v[224:225]
	v_pk_add_f32 v[144:145], v[144:145], v[226:227]
	v_pk_add_f32 v[146:147], v[146:147], v[228:229]
	v_pk_fma_f32 v[140:141], v[98:99], v[140:141], v[148:149] neg_lo:[0,0,1] neg_hi:[0,0,1]
	v_pk_fma_f32 v[142:143], v[98:99], v[142:143], v[150:151] neg_lo:[0,0,1] neg_hi:[0,0,1]
	v_pk_fma_f32 v[144:145], v[98:99], v[144:145], v[152:153] neg_lo:[0,0,1] neg_hi:[0,0,1]
	v_pk_fma_f32 v[146:147], v[98:99], v[146:147], v[154:155] neg_lo:[0,0,1] neg_hi:[0,0,1]
	v_cvt_pk_bf16_f32 v156, v140, v141
	v_cvt_pk_bf16_f32 v157, v142, v143
	v_cvt_pk_bf16_f32 v158, v144, v145
	v_cvt_pk_bf16_f32 v159, v146, v147
	ds_write_b128 v160, v[156:159]
	v_add_u32_e32 v160, 0x2100, v160
	s_waitcnt vmcnt(2)
	s_cmp_le_u32 0, s48
	s_cbranch_scc0 .Lpl_f79
	v_and_b32_e32 v237, 0xffff0000, v233
	v_lshlrev_b32_e32 v236, 16, v233
	v_and_b32_e32 v235, 0xffff0000, v232
	v_lshlrev_b32_e32 v234, 16, v232
	v_and_b32_e32 v233, 0xffff0000, v231
	v_lshlrev_b32_e32 v232, 16, v231
	v_and_b32_e32 v231, 0xffff0000, v230
	v_lshlrev_b32_e32 v230, 16, v230
.Lpl_f79:
	v_mov_b64_e32 v[148:149], v[230:231]
	v_mov_b64_e32 v[150:151], v[232:233]
	v_mov_b64_e32 v[152:153], v[234:235]
	v_mov_b64_e32 v[154:155], v[236:237]
	v_pk_add_f32 v[140:141], v[230:231], 0
	v_pk_add_f32 v[142:143], v[232:233], 0
	v_pk_add_f32 v[144:145], v[234:235], 0
	v_pk_add_f32 v[146:147], v[236:237], 0
	s_waitcnt vmcnt(0)
	s_cmp_le_u32 1, s48
	s_cbranch_scc0 .Lpl_f80
	v_and_b32_e32 v245, 0xffff0000, v241
	v_lshlrev_b32_e32 v244, 16, v241
	v_and_b32_e32 v243, 0xffff0000, v240
	v_lshlrev_b32_e32 v242, 16, v240
	v_and_b32_e32 v241, 0xffff0000, v239
	v_lshlrev_b32_e32 v240, 16, v239
	v_and_b32_e32 v239, 0xffff0000, v238
	v_lshlrev_b32_e32 v238, 16, v238
.Lpl_f80:
	v_pk_add_f32 v[140:141], v[140:141], v[238:239]
	v_pk_add_f32 v[142:143], v[142:143], v[240:241]
	v_pk_add_f32 v[144:145], v[144:145], v[242:243]
	v_pk_add_f32 v[146:147], v[146:147], v[244:245]
	v_pk_fma_f32 v[140:141], v[98:99], v[140:141], v[148:149] neg_lo:[0,0,1] neg_hi:[0,0,1]
	v_pk_fma_f32 v[142:143], v[98:99], v[142:143], v[150:151] neg_lo:[0,0,1] neg_hi:[0,0,1]
	v_pk_fma_f32 v[144:145], v[98:99], v[144:145], v[152:153] neg_lo:[0,0,1] neg_hi:[0,0,1]
	v_pk_fma_f32 v[146:147], v[98:99], v[146:147], v[154:155] neg_lo:[0,0,1] neg_hi:[0,0,1]
	v_cvt_pk_bf16_f32 v156, v140, v141
	v_cvt_pk_bf16_f32 v157, v142, v143
	v_cvt_pk_bf16_f32 v158, v144, v145
	v_cvt_pk_bf16_f32 v159, v146, v147
	ds_write_b128 v160, v[156:159]
	v_add_u32_e32 v160, 0x2100, v160
.Lpl_done:
.LBB0_1167:
	s_or_b64 exec, exec, s[10:11]
